# NA loop: cross-half max via v_permlane32_swap instead of ds_bpermute
# baseline (speedup 1.0000x reference)
; #define MFMA(a, b, c) __builtin_amdgcn_mfma_f32_32x32x16_bf16((a), (b), (c), 0, 0, 0)
; DI float fexp2(float x) { return __builtin_amdgcn_exp2f(x); }
; DI void flash_pass_na(f32x16 (&o)[2], const u16* __restrict__ Qp, const u16* __restrict__ Kb, int ldk,
;                       const u16* __restrict__ Vt, int S, int tile0, int ntiles, char* lds, int wlo, int whi,
;                       const float* bias_lds, int qrow, int rs_q, int qcol, int cs0) {
;     ...
;     if (kr >= wlo && kr <= whi) {
;       f32x16 s0;
; #pragma unroll
;       for (int i = 0; i < 16; ++i) s0[i] = 0.f;
;       {
;         bf16x8 ka[4];
; #pragma unroll
;         for (int ks = 0; ks < 4; ++ks) ka[ks] = *(const bf16x8*)(st + krow * 128 + (((2 * ks + h) ^ ksw) << 4));
;         asm volatile("" ::: "memory");
; #pragma unroll
;         for (int ks = 0; ks < 4; ++ks) s0 = MFMA(ka[ks], q[ks], s0);
;       }
;       bf16x8 vf[2][2];
; #pragma unroll
;       for (int c2 = 0; c2 < 2; ++c2) {
;         const int co = ((vch0 + 2 * c2 + h) ^ vsw) << 4;
; #pragma unroll
;         for (int mv = 0; mv < 2; ++mv) vf[c2][mv] = *(const bf16x8*)(st + 8192 + (mv * 32 + r) * 128 + co);
;       }
;       asm volatile("" ::: "memory");
;       const bool rowok = (kr >= rs_q) && (kr <= rs_q + 7);
;       const int bidx = rowok ? ((kr - qrow + 7) * 31 + dcb) : 64;
;       float t[16];
; #pragma unroll
;       for (int i = 0; i < 16; ++i) {
;         const int j = i >> 2;
;         const int kco = 16 * (j >> 1) + 4 * (j & 1) + (i & 3);
;         const bool ok = navalid[i] && rowok;
;         const float bv = bias_lds[ok ? (bidx + kco) : 0];
;         t[i] = ok ? (s0[i] + bv) : -INFINITY;
;       }
;       float mx = t[0];
; #pragma unroll
;       for (int e = 1; e < 16; ++e) mx = fmaxf(mx, t[e]);
;       mx = fmaxf(mx, __shfl_xor(mx, 32));
;       if (__builtin_amdgcn_ballot_w64(mx > m_run + 8.f) != 0ull) {
;         const float m_new = fmaxf(m_run, mx);
;         const float alpha = fexp2(m_run - m_new);
;         l_run *= alpha;
;         m_run = m_new;
; #pragma unroll
;         for (int mv = 0; mv < 2; ++mv)
; #pragma unroll
;           for (int i = 0; i < 16; ++i) o[mv][i] *= alpha;
;       }
.LBB0_119:
	s_add_i32 s70, s65, s69
	v_cmp_ge_u32_e32 vcc, s70, v115
	v_cmp_le_u32_e64 s[46:47], s70, v116
	s_and_b64 s[46:47], vcc, s[46:47]
	s_and_saveexec_b64 s[10:11], s[46:47]
	s_cbranch_execz .LBB0_155
	s_bitcmp1_b32 s69, 0
	s_cselect_b32 s46, 0x6000, 0
	v_add_u32_e32 v78, s46, v117
	v_add_u32_e32 v34, v78, v120
	ds_read_b128 v[34:37], v34
	v_add_u32_e32 v38, v78, v121
	ds_read_b128 v[74:77], v38
	v_add_u32_e32 v79, v78, v122
	v_add_u32_e32 v78, v78, v123
	ds_read_b128 v[128:131], v78
	v_or_b32_e32 v80, s46, v125
	v_cmp_ge_u32_e32 vcc, s70, v114
	s_waitcnt lgkmcnt(2)
	v_mfma_f32_32x32x16_bf16 v[34:49], v[34:37], v[50:53], 0
	s_waitcnt lgkmcnt(1)
	v_mfma_f32_32x32x16_bf16 v[34:49], v[74:77], v[54:57], v[34:49]
	ds_read_b128 v[74:77], v79
	v_or_b32_e32 v79, s46, v124
	v_add_u32_e32 v79, v79, v118
	v_cmp_le_u32_e64 s[46:47], s70, v119
	s_and_b64 vcc, vcc, s[46:47]
	s_and_b64 s[70:71], s[12:13], vcc
	s_waitcnt lgkmcnt(0)
	v_mfma_f32_32x32x16_bf16 v[34:49], v[74:77], v[58:61], v[34:49]
	v_add_u32_e32 v74, v80, v118
	ds_read_b128 v[86:89], v79 offset:8192
	ds_read_b128 v[82:85], v79 offset:12288
	ds_read_b128 v[78:81], v74 offset:8192
	ds_read_b128 v[74:77], v74 offset:12288
	v_mfma_f32_32x32x16_bf16 v[34:49], v[128:131], v[62:65], v[34:49]
	v_cndmask_b32_e32 v128, 64, v126, vcc
	v_lshlrev_b32_e32 v132, 2, v128
	v_mov_b32_e32 v133, 0xff800000
	ds_read_b32 v134, v132 offset:49152
	ds_read_b32 v135, v132 offset:49156
	ds_read_b32 v136, v132 offset:49160
	ds_read_b32 v137, v132 offset:49164
	ds_read_b32 v138, v132 offset:49168
	ds_read_b32 v139, v132 offset:49172
	ds_read_b32 v140, v132 offset:49176
	ds_read_b32 v141, v132 offset:49180
	ds_read_b32 v142, v132 offset:49216
	ds_read_b32 v143, v132 offset:49220
	ds_read_b32 v144, v132 offset:49224
	ds_read_b32 v145, v132 offset:49228
	ds_read_b32 v146, v132 offset:49232
	ds_read_b32 v147, v132 offset:49236
	ds_read_b32 v148, v132 offset:49240
	ds_read_b32 v149, v132 offset:49244
	s_waitcnt lgkmcnt(0)
	s_and_b64 s[70:71], s[12:13], vcc
	v_add_f32_e32 v129, v34, v134
	v_cndmask_b32_e64 v129, v133, v129, s[70:71]
	s_and_b64 s[70:71], s[14:15], vcc
	v_add_f32_e32 v128, v35, v135
	v_cndmask_b32_e64 v128, v133, v128, s[70:71]
	s_and_b64 s[70:71], s[16:17], vcc
	v_add_f32_e32 v35, v36, v136
	v_cndmask_b32_e64 v35, v133, v35, s[70:71]
	s_and_b64 s[70:71], s[18:19], vcc
	v_add_f32_e32 v34, v37, v137
	v_cndmask_b32_e64 v34, v133, v34, s[70:71]
	s_and_b64 s[70:71], s[20:21], vcc
	v_add_f32_e32 v37, v38, v138
	v_cndmask_b32_e64 v37, v133, v37, s[70:71]
	s_and_b64 s[70:71], s[22:23], vcc
	v_add_f32_e32 v36, v39, v139
	v_cndmask_b32_e64 v36, v133, v36, s[70:71]
	s_and_b64 s[70:71], s[24:25], vcc
	v_add_f32_e32 v130, v40, v140
	v_cndmask_b32_e64 v130, v133, v130, s[70:71]
	s_and_b64 s[70:71], s[26:27], vcc
	v_add_f32_e32 v38, v41, v141
	v_cndmask_b32_e64 v38, v133, v38, s[70:71]
	s_and_b64 s[70:71], s[28:29], vcc
	v_add_f32_e32 v41, v42, v142
	v_cndmask_b32_e64 v41, v133, v41, s[70:71]
	s_and_b64 s[70:71], s[30:31], vcc
	v_add_f32_e32 v40, v43, v143
	v_cndmask_b32_e64 v40, v133, v40, s[70:71]
	s_and_b64 s[70:71], s[34:35], vcc
	v_add_f32_e32 v131, v44, v144
	v_cndmask_b32_e64 v131, v133, v131, s[70:71]
	s_and_b64 s[70:71], s[36:37], vcc
	v_add_f32_e32 v39, v45, v145
	v_cndmask_b32_e64 v39, v133, v39, s[70:71]
	s_and_b64 s[70:71], s[38:39], vcc
	v_add_f32_e32 v43, v46, v146
	v_cndmask_b32_e64 v43, v133, v43, s[70:71]
	s_and_b64 s[70:71], s[40:41], vcc
	v_add_f32_e32 v42, v47, v147
	v_cndmask_b32_e64 v42, v133, v42, s[70:71]
	s_and_b64 s[70:71], s[42:43], vcc
	v_add_f32_e32 v45, v48, v148
	v_cndmask_b32_e64 v45, v133, v45, s[70:71]
	s_and_b64 s[70:71], s[44:45], vcc
	v_add_f32_e32 v44, v49, v149
	v_cndmask_b32_e64 v44, v133, v44, s[70:71]
	v_max_f32_e32 v46, v128, v128
	v_max_f32_e32 v47, v129, v129
	v_max_f32_e32 v46, v47, v46
	v_max3_f32 v46, v46, v35, v34
	v_max3_f32 v46, v46, v37, v36
	v_max3_f32 v46, v46, v130, v38
	v_max3_f32 v46, v46, v41, v40
	v_max3_f32 v46, v46, v131, v39
	v_max3_f32 v46, v46, v43, v42
	v_max3_f32 v46, v46, v45, v44
	v_mov_b32_e32 v47, v46
	s_nop 1
	v_permlane32_swap_b32_e32 v46, v47
	v_max_f32_e32 v46, v46, v47
	v_add_f32_e32 v47, 0x41000000, v127
	v_cmp_gt_f32_e32 vcc, v46, v47
	s_cbranch_vccz .LBB0_154
	v_max_f32_e32 v46, v46, v46
	v_max_f32_e32 v47, v127, v127
	v_max_f32_e32 v47, v47, v46
	v_sub_f32_e32 v46, v127, v47
	v_exp_f32_e32 v46, v46
	v_mov_b32_e32 v127, v47
	v_pk_mul_f32 v[16:17], v[16:17], v[46:47] op_sel_hi:[1,0]
	v_pk_mul_f32 v[14:15], v[14:15], v[46:47] op_sel_hi:[1,0]
	v_pk_mul_f32 v[12:13], v[12:13], v[46:47] op_sel_hi:[1,0]
	v_pk_mul_f32 v[10:11], v[10:11], v[46:47] op_sel_hi:[1,0]
	v_pk_mul_f32 v[8:9], v[8:9], v[46:47] op_sel_hi:[1,0]
	v_pk_mul_f32 v[6:7], v[6:7], v[46:47] op_sel_hi:[1,0]
	v_pk_mul_f32 v[4:5], v[4:5], v[46:47] op_sel_hi:[1,0]
	v_pk_mul_f32 v[2:3], v[2:3], v[46:47] op_sel_hi:[1,0]
	v_pk_mul_f32 v[32:33], v[32:33], v[46:47] op_sel_hi:[1,0]
	v_pk_mul_f32 v[30:31], v[30:31], v[46:47] op_sel_hi:[1,0]
	v_pk_mul_f32 v[28:29], v[28:29], v[46:47] op_sel_hi:[1,0]
	v_pk_mul_f32 v[26:27], v[26:27], v[46:47] op_sel_hi:[1,0]
	v_pk_mul_f32 v[24:25], v[24:25], v[46:47] op_sel_hi:[1,0]
	v_pk_mul_f32 v[22:23], v[22:23], v[46:47] op_sel_hi:[1,0]
	v_pk_mul_f32 v[20:21], v[20:21], v[46:47] op_sel_hi:[1,0]
	v_pk_mul_f32 v[18:19], v[18:19], v[46:47] op_sel_hi:[1,0]
	v_mul_f32_e32 v0, v0, v46
